# phase 0 fold A: 8 MFMA steps' operand loads batched into two groups under one wait each (was 16 dependent round trips)
# speedup vs baseline: 1.0088x; 1.0047x over previous
.LBB0_44:
	s_andn2_b64 vcc, exec, s[56:57]
	s_cbranch_vccnz .LBB0_46
	v_lshl_add_u32 v0, s5, 3, v89
	v_ashrrev_i32_e32 v72, 5, v0
	v_lshlrev_b32_e32 v0, 2, v0
	v_and_b32_e32 v65, 0x60, v0
	v_or_b32_e32 v0, v65, v79
	v_lshlrev_b32_e32 v18, 4, v0
	v_ashrrev_i32_e32 v73, 31, v72
	v_lshl_add_u64 v[0:1], v[18:19], 0, v[72:73]
	v_lshlrev_b64 v[0:1], 9, v[0:1]
	v_lshl_add_u64 v[74:75], v[28:29], 0, v[0:1]
	v_add_u32_e32 v0, v72, v70
	s_movk_i32 s56, 0x300
	v_mad_i64_i32 v[76:77], s[56:57], v0, s56, v[30:31]
	s_waitcnt lgkmcnt(0)
	v_lshlrev_b32_e32 v18, 7, v72
	v_or3_b32 v72, v18, v87, v65
	v_ashrrev_i32_e32 v73, 31, v72
	global_load_dwordx4 v[200:203], v[74:75], off
	global_load_dwordx4 v[204:207], v[74:75], off offset:16
	global_load_dwordx4 v[208:211], v[76:77], off
	global_load_dwordx4 v[212:215], v[76:77], off offset:16
	global_load_dwordx4 v[216:219], v[74:75], off offset:64
	global_load_dwordx4 v[220:223], v[74:75], off offset:80
	global_load_dwordx4 v[224:227], v[76:77], off offset:64
	global_load_dwordx4 v[228:231], v[76:77], off offset:80
	global_load_dwordx4 v[232:235], v[74:75], off offset:128
	global_load_dwordx4 v[236:239], v[74:75], off offset:144
	global_load_dwordx4 v[240:243], v[76:77], off offset:128
	global_load_dwordx4 v[244:247], v[76:77], off offset:144
	global_load_dwordx4 v[248:251], v[74:75], off offset:192
	global_load_dwordx4 v[96:99], v[74:75], off offset:208
	global_load_dwordx4 v[100:103], v[76:77], off offset:192
	global_load_dwordx4 v[104:107], v[76:77], off offset:208
	s_waitcnt vmcnt(0)
	v_cvt_pk_bf16_f32 v200, v200, v201
	v_cvt_pk_bf16_f32 v201, v202, v203
	v_cvt_pk_bf16_f32 v202, v204, v205
	v_cvt_pk_bf16_f32 v203, v206, v207
	v_cvt_pk_bf16_f32 v208, v208, v209
	v_cvt_pk_bf16_f32 v209, v210, v211
	v_cvt_pk_bf16_f32 v210, v212, v213
	v_cvt_pk_bf16_f32 v211, v214, v215
	v_cvt_pk_bf16_f32 v216, v216, v217
	v_cvt_pk_bf16_f32 v217, v218, v219
	v_cvt_pk_bf16_f32 v218, v220, v221
	v_cvt_pk_bf16_f32 v219, v222, v223
	v_cvt_pk_bf16_f32 v224, v224, v225
	v_cvt_pk_bf16_f32 v225, v226, v227
	v_cvt_pk_bf16_f32 v226, v228, v229
	v_cvt_pk_bf16_f32 v227, v230, v231
	v_cvt_pk_bf16_f32 v232, v232, v233
	v_cvt_pk_bf16_f32 v233, v234, v235
	v_cvt_pk_bf16_f32 v234, v236, v237
	v_cvt_pk_bf16_f32 v235, v238, v239
	v_cvt_pk_bf16_f32 v240, v240, v241
	v_cvt_pk_bf16_f32 v241, v242, v243
	v_cvt_pk_bf16_f32 v242, v244, v245
	v_cvt_pk_bf16_f32 v243, v246, v247
	v_cvt_pk_bf16_f32 v248, v248, v249
	v_cvt_pk_bf16_f32 v249, v250, v251
	v_cvt_pk_bf16_f32 v250, v96, v97
	v_cvt_pk_bf16_f32 v251, v98, v99
	v_cvt_pk_bf16_f32 v100, v100, v101
	v_cvt_pk_bf16_f32 v101, v102, v103
	v_cvt_pk_bf16_f32 v102, v104, v105
	v_cvt_pk_bf16_f32 v103, v106, v107
	s_nop 1
	v_mfma_f32_32x32x16_bf16 v[0:15], v[200:203], v[208:211], 0
	v_mfma_f32_32x32x16_bf16 v[0:15], v[216:219], v[224:227], v[0:15]
	v_mfma_f32_32x32x16_bf16 v[0:15], v[232:235], v[240:243], v[0:15]
	v_mfma_f32_32x32x16_bf16 v[0:15], v[248:251], v[100:103], v[0:15]
	global_load_dwordx4 v[200:203], v[74:75], off offset:256
	global_load_dwordx4 v[204:207], v[74:75], off offset:272
	global_load_dwordx4 v[208:211], v[76:77], off offset:256
	global_load_dwordx4 v[212:215], v[76:77], off offset:272
	global_load_dwordx4 v[216:219], v[74:75], off offset:320
	global_load_dwordx4 v[220:223], v[74:75], off offset:336
	global_load_dwordx4 v[224:227], v[76:77], off offset:320
	global_load_dwordx4 v[228:231], v[76:77], off offset:336
	global_load_dwordx4 v[232:235], v[74:75], off offset:384
	global_load_dwordx4 v[236:239], v[74:75], off offset:400
	global_load_dwordx4 v[240:243], v[76:77], off offset:384
	global_load_dwordx4 v[244:247], v[76:77], off offset:400
	global_load_dwordx4 v[248:251], v[74:75], off offset:448
	global_load_dwordx4 v[96:99], v[74:75], off offset:464
	global_load_dwordx4 v[100:103], v[76:77], off offset:448
	global_load_dwordx4 v[104:107], v[76:77], off offset:464
	s_waitcnt vmcnt(0)
	v_cvt_pk_bf16_f32 v200, v200, v201
	v_cvt_pk_bf16_f32 v201, v202, v203
	v_cvt_pk_bf16_f32 v202, v204, v205
	v_cvt_pk_bf16_f32 v203, v206, v207
	v_cvt_pk_bf16_f32 v208, v208, v209
	v_cvt_pk_bf16_f32 v209, v210, v211
	v_cvt_pk_bf16_f32 v210, v212, v213
	v_cvt_pk_bf16_f32 v211, v214, v215
	v_cvt_pk_bf16_f32 v216, v216, v217
	v_cvt_pk_bf16_f32 v217, v218, v219
	v_cvt_pk_bf16_f32 v218, v220, v221
	v_cvt_pk_bf16_f32 v219, v222, v223
	v_cvt_pk_bf16_f32 v224, v224, v225
	v_cvt_pk_bf16_f32 v225, v226, v227
	v_cvt_pk_bf16_f32 v226, v228, v229
	v_cvt_pk_bf16_f32 v227, v230, v231
	v_cvt_pk_bf16_f32 v232, v232, v233
	v_cvt_pk_bf16_f32 v233, v234, v235
	v_cvt_pk_bf16_f32 v234, v236, v237
	v_cvt_pk_bf16_f32 v235, v238, v239
	v_cvt_pk_bf16_f32 v240, v240, v241
	v_cvt_pk_bf16_f32 v241, v242, v243
	v_cvt_pk_bf16_f32 v242, v244, v245
	v_cvt_pk_bf16_f32 v243, v246, v247
	v_cvt_pk_bf16_f32 v248, v248, v249
	v_cvt_pk_bf16_f32 v249, v250, v251
	v_cvt_pk_bf16_f32 v250, v96, v97
	v_cvt_pk_bf16_f32 v251, v98, v99
	v_cvt_pk_bf16_f32 v100, v100, v101
	v_cvt_pk_bf16_f32 v101, v102, v103
	v_cvt_pk_bf16_f32 v102, v104, v105
	v_cvt_pk_bf16_f32 v103, v106, v107
	s_nop 1
	v_mfma_f32_32x32x16_bf16 v[0:15], v[200:203], v[208:211], v[0:15]
	v_mfma_f32_32x32x16_bf16 v[0:15], v[216:219], v[224:227], v[0:15]
	v_mfma_f32_32x32x16_bf16 v[0:15], v[232:235], v[240:243], v[0:15]
	v_mfma_f32_32x32x16_bf16 v[0:15], v[248:251], v[100:103], v[0:15]
	v_lshlrev_b64 v[74:75], 9, v[72:73]
	v_lshl_add_u64 v[74:75], v[22:23], 0, v[74:75]
	s_nop 9
	v_cvt_pk_bf16_f32 v0, v0, s0
	global_store_short v[74:75], v0, off
	v_or_b32_e32 v0, 1, v72
	v_cvt_pk_bf16_f32 v18, v1, s0
	v_ashrrev_i32_e32 v1, 31, v0
	v_lshlrev_b64 v[0:1], 9, v[0:1]
	v_lshl_add_u64 v[0:1], v[22:23], 0, v[0:1]
	global_store_short v[0:1], v18, off
	v_or_b32_e32 v0, 2, v72
	v_ashrrev_i32_e32 v1, 31, v0
	v_lshlrev_b64 v[0:1], 9, v[0:1]
	v_cvt_pk_bf16_f32 v2, v2, s0
	v_lshl_add_u64 v[0:1], v[22:23], 0, v[0:1]
	global_store_short v[0:1], v2, off
	v_or_b32_e32 v0, 3, v72
	v_ashrrev_i32_e32 v1, 31, v0
	v_lshlrev_b64 v[0:1], 9, v[0:1]
	v_cvt_pk_bf16_f32 v2, v3, s0
	v_lshl_add_u64 v[0:1], v[22:23], 0, v[0:1]
	global_store_short v[0:1], v2, off
	v_or_b32_e32 v0, 8, v72
	v_ashrrev_i32_e32 v1, 31, v0
	v_lshlrev_b64 v[0:1], 9, v[0:1]
	v_cvt_pk_bf16_f32 v2, v4, s0
	v_lshl_add_u64 v[0:1], v[22:23], 0, v[0:1]
	global_store_short v[0:1], v2, off
	v_or_b32_e32 v0, 9, v72
	v_ashrrev_i32_e32 v1, 31, v0
	v_lshlrev_b64 v[0:1], 9, v[0:1]
	v_cvt_pk_bf16_f32 v2, v5, s0
	v_lshl_add_u64 v[0:1], v[22:23], 0, v[0:1]
	global_store_short v[0:1], v2, off
	v_or_b32_e32 v0, 10, v72
	v_ashrrev_i32_e32 v1, 31, v0
	v_lshlrev_b64 v[0:1], 9, v[0:1]
	v_cvt_pk_bf16_f32 v2, v6, s0
	v_lshl_add_u64 v[0:1], v[22:23], 0, v[0:1]
	global_store_short v[0:1], v2, off
	v_or_b32_e32 v0, 11, v72
	v_ashrrev_i32_e32 v1, 31, v0
	v_lshlrev_b64 v[0:1], 9, v[0:1]
	v_cvt_pk_bf16_f32 v2, v7, s0
	v_lshl_add_u64 v[0:1], v[22:23], 0, v[0:1]
	global_store_short v[0:1], v2, off
	v_or_b32_e32 v0, 16, v72
	v_ashrrev_i32_e32 v1, 31, v0
	v_lshlrev_b64 v[0:1], 9, v[0:1]
	v_cvt_pk_bf16_f32 v2, v8, s0
	v_lshl_add_u64 v[0:1], v[22:23], 0, v[0:1]
	global_store_short v[0:1], v2, off
	v_or_b32_e32 v0, 17, v72
	v_ashrrev_i32_e32 v1, 31, v0
	v_lshlrev_b64 v[0:1], 9, v[0:1]
	v_cvt_pk_bf16_f32 v2, v9, s0
	v_lshl_add_u64 v[0:1], v[22:23], 0, v[0:1]
	global_store_short v[0:1], v2, off
	v_or_b32_e32 v0, 18, v72
	v_ashrrev_i32_e32 v1, 31, v0
	v_lshlrev_b64 v[0:1], 9, v[0:1]
	v_cvt_pk_bf16_f32 v2, v10, s0
	v_lshl_add_u64 v[0:1], v[22:23], 0, v[0:1]
	global_store_short v[0:1], v2, off
	v_or_b32_e32 v0, 19, v72
	v_ashrrev_i32_e32 v1, 31, v0
	v_lshlrev_b64 v[0:1], 9, v[0:1]
	v_cvt_pk_bf16_f32 v2, v11, s0
	v_lshl_add_u64 v[0:1], v[22:23], 0, v[0:1]
	global_store_short v[0:1], v2, off
	v_or_b32_e32 v0, 24, v72
	v_ashrrev_i32_e32 v1, 31, v0
	v_lshlrev_b64 v[0:1], 9, v[0:1]
	v_cvt_pk_bf16_f32 v2, v12, s0
	v_lshl_add_u64 v[0:1], v[22:23], 0, v[0:1]
	global_store_short v[0:1], v2, off
	v_or_b32_e32 v0, 25, v72
	v_ashrrev_i32_e32 v1, 31, v0
	v_lshlrev_b64 v[0:1], 9, v[0:1]
	v_cvt_pk_bf16_f32 v2, v13, s0
	v_lshl_add_u64 v[0:1], v[22:23], 0, v[0:1]
	global_store_short v[0:1], v2, off
	v_or_b32_e32 v0, 26, v72
	v_ashrrev_i32_e32 v1, 31, v0
	v_lshlrev_b64 v[0:1], 9, v[0:1]
	v_cvt_pk_bf16_f32 v2, v14, s0
	v_lshl_add_u64 v[0:1], v[22:23], 0, v[0:1]
	global_store_short v[0:1], v2, off
	v_or_b32_e32 v0, 27, v72
	v_ashrrev_i32_e32 v1, 31, v0
	v_lshlrev_b64 v[0:1], 9, v[0:1]
	v_cvt_pk_bf16_f32 v2, v15, s0
	v_lshl_add_u64 v[0:1], v[22:23], 0, v[0:1]
	global_store_short v[0:1], v2, off
